# A1 attention: waves 4-7 run a staggered stream (softmax of tile j+1 as a VALU-only block at tile start, then QK, then PV) so each SIMD pairs an MFMA-only wave with a VALU wave
# speedup vs baseline: 1.0063x; 1.0063x over previous
; DI void rope_sc(float pos, int j, float& sn, float& cs) {
;   const float fr = exp2f(-(float)j * (LOG2_THETA / 32.f));
;   float tr = pos * fr * INV_2PI;
;   tr -= floorf(tr);
;   sn = __builtin_amdgcn_sinf(tr);
;   cs = __builtin_amdgcn_cosf(tr);
; }
; template <int NHQ, int NHKV>
; DI void attn_phase_l1(const u16* __restrict__ Q, const u16* __restrict__ K, const u16* __restrict__ Vt, u16* __restrict__ O, const float* __restrict__ qg, char* smem, const int wv) {
;     ...
;   for (int item = (G_ % 8 == 0) ? (b_ % 8) * (G_ / 8) + b_ / 8 : b_; item < NF; item += G_) {
;     const int hq = (item >> 4) % NHQ, sq = item / (16 * NHQ), q0 = NMETA + 256 * (item & 15);
;     const u16* Kb = K + (size_t)(sq * L) * LDK + (hq / (NHQ / NHKV)) * DQK;
;     const u16* Vb = Vt + (size_t)((sq * NHKV + hq / (NHQ / NHKV)) * 128) * LP;
;     const int pq = q0 + wave * 32 + r32;
;     {
;       const u16* qrow = Q + (size_t)(sq * L + pq) * 1280 + hq * DQK + hh * 8;
;       int hho = hh; asm volatile("" : "+v"(hho));
;       float ssq = 0.f;
; #pragma unroll
;       for (int i = 0; i < NS; ++i) {
;         qf[i] = *(const bf16x8*)(qrow + 16 * i);
;         float t8[8]; unpack8(__builtin_bit_cast(u32x4, qf[i]), t8);
; #pragma unroll
;         for (int e = 0; e < 8; ++e) ssq += t8[e] * t8[e];
;       }
;       ssq = xhalf_sum(ssq);
;       const float rn = rsqrtf(ssq * (1.f / DQK) + EPS) * (0.08838834764831845f * 1.4426950408889634f);
;     ...
;       const float prow = (float)((pq - NMETA) >> 6), pcol = (float)((pq - NMETA) & 63);
;       A_QROPE(0, 2, 0, prow); A_QROPE(1, 3, 1, prow);
;       A_QROPE(4, 6, 0, pcol); A_QROPE(5, 7, 1, pcol);
.LBB0_1216:
	s_ashr_i32 s18, s28, 4
	s_lshr_b32 s19, s18, 29
	s_add_i32 s19, s18, s19
	s_and_b32 s19, s19, -8
	s_sub_i32 s24, s18, s19
	s_ashr_i32 s18, s28, 31
	s_lshr_b32 s18, s18, 25
	s_add_i32 s18, s28, s18
	s_ashr_i32 s41, s18, 7
	s_lshl_b32 s18, s28, 8
	s_and_b32 s25, s18, 0xf00
	s_mul_i32 s18, s41, 0x1010
	s_ashr_i32 s19, s18, 31
	s_lshl_b64 s[20:21], s[18:19], 9
	s_bfe_i32 s19, s24, 0x80000
	s_bfe_u32 s19, s19, 0x2000d
	s_add_i32 s19, s24, s19
	s_sext_i32_i8 s19, s19
	s_lshl_b32 s19, s19, 5
	v_add_u32_e32 v2, s25, v202
	s_and_b32 s22, s19, 0xffffff80
	s_lshl_b32 s19, s41, 8
	v_add_u32_e32 v0, s18, v2
	s_add_i32 s42, s22, s19
	v_mad_i64_i32 v[0:1], s[18:19], v0, s35, v[168:169]
	s_lshl_b32 s18, s24, 7
	s_ashr_i32 s19, s18, 31
	v_lshl_add_u64 v[0:1], s[18:19], 1, v[0:1]
	v_mov_b32_e32 v3, v200
	v_lshl_add_u64 v[0:1], v[0:1], 0, v[170:171]
	global_load_dwordx4 v[68:71], v[0:1], off
	global_load_dwordx4 v[76:79], v[0:1], off offset:32
	global_load_dwordx4 v[64:67], v[0:1], off offset:64
	global_load_dwordx4 v[72:75], v[0:1], off offset:96
	global_load_dwordx4 v[84:87], v[0:1], off offset:128
	global_load_dwordx4 v[92:95], v[0:1], off offset:160
	global_load_dwordx4 v[80:83], v[0:1], off offset:192
	global_load_dwordx4 v[88:91], v[0:1], off offset:224
	v_lshlrev_b32_e32 v17, 3, v3
	v_cvt_f32_i32_e32 v1, v17
	v_add_u32_e32 v173, -16, v2
	v_ashrrev_i32_e32 v0, 6, v173
	v_cvt_f32_i32_e32 v18, v0
	v_mul_f32_e32 v0, 0xbed49a78, v1
	v_cmp_gt_f32_e32 vcc, s36, v0
	global_load_dwordx4 v[28:31], v[166:167], off
	global_load_dwordx4 v[24:27], v[166:167], off offset:16
	v_cndmask_b32_e32 v0, 0, v208, vcc
	v_fmac_f32_e32 v0, 0xbed49a78, v1
	v_exp_f32_e32 v0, v0
	v_cndmask_b32_e32 v1, 0, v209, vcc
	global_load_dwordx4 v[36:39], v[166:167], off offset:128
	global_load_dwordx4 v[32:35], v[166:167], off offset:144
	v_and_b32_e32 v16, 63, v173
	v_ldexp_f32 v19, v0, v1
	v_or_b32_e32 v1, 1, v17
	v_cvt_f32_i32_e32 v1, v1
	v_mul_f32_e32 v0, v19, v18
	v_mul_f32_e32 v2, 0.15915494, v0
	v_floor_f32_e32 v2, v2
	v_fma_f32 v0, v0, 0.15915494, -v2
	v_mul_f32_e32 v2, 0xbed49a78, v1
	v_cmp_gt_f32_e32 vcc, s36, v2
	v_sin_f32_e32 v96, v0
	v_cos_f32_e32 v98, v0
	v_cndmask_b32_e32 v2, 0, v208, vcc
	v_fmac_f32_e32 v2, 0xbed49a78, v1
	v_exp_f32_e32 v1, v2
	v_cndmask_b32_e32 v0, 0, v209, vcc
	v_cvt_f32_ubyte0_e32 v155, v16
	v_mul_f32_e32 v16, v19, v155
	v_ldexp_f32 v20, v1, v0
	v_or_b32_e32 v1, 2, v17
	v_cvt_f32_i32_e32 v1, v1
	v_mul_f32_e32 v0, v20, v18
	v_mul_f32_e32 v2, 0.15915494, v0
	v_floor_f32_e32 v2, v2
	v_fma_f32 v0, v0, 0.15915494, -v2
	v_mul_f32_e32 v2, 0xbed49a78, v1
	v_cmp_gt_f32_e32 vcc, s36, v2
	v_sin_f32_e32 v97, v0
	v_cos_f32_e32 v99, v0
	v_cndmask_b32_e32 v2, 0, v208, vcc
	v_fmac_f32_e32 v2, 0xbed49a78, v1
	v_exp_f32_e32 v1, v2
	v_cndmask_b32_e32 v0, 0, v209, vcc
	s_ashr_i32 s23, s22, 31
	s_add_u32 s24, s29, s20
	v_ldexp_f32 v21, v1, v0
	v_or_b32_e32 v1, 3, v17
	v_cvt_f32_i32_e32 v1, v1
	v_mul_f32_e32 v0, v21, v18
	v_mul_f32_e32 v2, 0.15915494, v0
	v_floor_f32_e32 v2, v2
	v_fma_f32 v0, v0, 0.15915494, -v2
	v_mul_f32_e32 v2, 0xbed49a78, v1
	v_cmp_gt_f32_e32 vcc, s36, v2
	v_sin_f32_e32 v100, v0
	v_cos_f32_e32 v102, v0
	v_cndmask_b32_e32 v2, 0, v208, vcc
	v_fmac_f32_e32 v2, 0xbed49a78, v1
	v_exp_f32_e32 v1, v2
	v_cndmask_b32_e32 v0, 0, v209, vcc
	s_addc_u32 s25, s30, s21
	s_lshl_b64 s[22:23], s[22:23], 1
	v_ldexp_f32 v22, v1, v0
	v_or_b32_e32 v1, 4, v17
	v_cvt_f32_i32_e32 v1, v1
	v_mul_f32_e32 v0, v22, v18
	v_mul_f32_e32 v2, 0.15915494, v0
	v_floor_f32_e32 v2, v2
	v_fma_f32 v0, v0, 0.15915494, -v2
	v_mul_f32_e32 v2, 0xbed49a78, v1
	v_cmp_gt_f32_e32 vcc, s36, v2
	v_sin_f32_e32 v101, v0
	v_cos_f32_e32 v103, v0
	v_cndmask_b32_e32 v2, 0, v208, vcc
	v_fmac_f32_e32 v2, 0xbed49a78, v1
	v_exp_f32_e32 v1, v2
	v_cndmask_b32_e32 v0, 0, v209, vcc
	s_waitcnt vmcnt(11)
	v_and_b32_e32 v223, 0xffff0000, v68
	v_lshlrev_b32_e32 v222, 16, v68
	v_ldexp_f32 v23, v1, v0
	v_or_b32_e32 v1, 5, v17
	v_cvt_f32_i32_e32 v1, v1
	v_mul_f32_e32 v0, v23, v18
	v_mul_f32_e32 v2, 0.15915494, v0
	v_floor_f32_e32 v2, v2
	v_fma_f32 v0, v0, 0.15915494, -v2
	v_mul_f32_e32 v2, 0xbed49a78, v1
	v_cmp_gt_f32_e32 vcc, s36, v2
	v_sin_f32_e32 v140, v0
	v_cos_f32_e32 v142, v0
	v_cndmask_b32_e32 v2, 0, v208, vcc
	v_fmac_f32_e32 v2, 0xbed49a78, v1
	v_exp_f32_e32 v1, v2
	v_cndmask_b32_e32 v0, 0, v209, vcc
	v_mul_f32_e32 v68, v223, v223
	s_waitcnt vmcnt(6)
	v_lshlrev_b32_e32 v158, 16, v95
	v_ldexp_f32 v40, v1, v0
	v_or_b32_e32 v1, 6, v17
	v_cvt_f32_i32_e32 v1, v1
	v_mul_f32_e32 v0, v40, v18
	v_mul_f32_e32 v2, 0.15915494, v0
	v_floor_f32_e32 v2, v2
	v_fma_f32 v0, v0, 0.15915494, -v2
	v_mul_f32_e32 v2, 0xbed49a78, v1
	v_cmp_gt_f32_e32 vcc, s36, v2
	v_sin_f32_e32 v141, v0
	v_cos_f32_e32 v143, v0
	v_cndmask_b32_e32 v2, 0, v208, vcc
	v_fmac_f32_e32 v2, 0xbed49a78, v1
	v_exp_f32_e32 v1, v2
	v_cndmask_b32_e32 v0, 0, v209, vcc
	v_and_b32_e32 v159, 0xffff0000, v95
	s_waitcnt vmcnt(4)
; DI void rope_sc(float pos, int j, float& sn, float& cs) {
;   const float fr = exp2f(-(float)j * (LOG2_THETA / 32.f));
;   float tr = pos * fr * INV_2PI;
;   tr -= floorf(tr);
;   sn = __builtin_amdgcn_sinf(tr);
;   cs = __builtin_amdgcn_cosf(tr);
; }
; template <int NHQ, int NHKV>
; DI void attn_phase_l1(const u16* __restrict__ Q, const u16* __restrict__ K, const u16* __restrict__ Vt, u16* __restrict__ O, const float* __restrict__ qg, char* smem, const int wv) {
;     ...
;       const float prow = (float)((pq - NMETA) >> 6), pcol = (float)((pq - NMETA) & 63);
;       A_QROPE(0, 2, 0, prow); A_QROPE(1, 3, 1, prow);
;       A_QROPE(4, 6, 0, pcol); A_QROPE(5, 7, 1, pcol);
	v_lshlrev_b32_e32 v156, 16, v91
	v_ldexp_f32 v41, v1, v0
	v_or_b32_e32 v1, 7, v17
	v_cvt_f32_i32_e32 v1, v1
	v_mul_f32_e32 v0, v41, v18
	v_mul_f32_e32 v2, 0.15915494, v0
	v_floor_f32_e32 v2, v2
	v_fma_f32 v0, v0, 0.15915494, -v2
	v_mul_f32_e32 v2, 0xbed49a78, v1
	v_cmp_gt_f32_e32 vcc, s36, v2
	v_sin_f32_e32 v180, v0
	v_cos_f32_e32 v182, v0
	v_cndmask_b32_e32 v2, 0, v208, vcc
	v_fmac_f32_e32 v2, 0xbed49a78, v1
	v_exp_f32_e32 v1, v2
	v_cndmask_b32_e32 v0, 0, v209, vcc
	v_and_b32_e32 v157, 0xffff0000, v91
	v_lshlrev_b32_e32 v174, 16, v94
	v_ldexp_f32 v42, v1, v0
	v_mul_f32_e32 v0, v42, v18
	v_mul_f32_e32 v1, 0.15915494, v0
	v_floor_f32_e32 v1, v1
	v_fma_f32 v0, v0, 0.15915494, -v1
	v_add_u32_e32 v1, 16, v17
	v_cvt_f32_i32_e32 v4, v1
	v_and_b32_e32 v175, 0xffff0000, v94
	v_lshlrev_b32_e32 v94, 16, v90
	v_and_b32_e32 v95, 0xffff0000, v90
	v_mul_f32_e32 v5, 0xbed49a78, v4
	v_cmp_gt_f32_e32 vcc, s36, v5
	v_lshlrev_b32_e32 v176, 16, v93
	v_and_b32_e32 v177, 0xffff0000, v93
	v_cndmask_b32_e32 v5, 0, v208, vcc
	v_fmac_f32_e32 v5, 0xbed49a78, v4
	v_exp_f32_e32 v43, v5
	v_cndmask_b32_e32 v44, 0, v209, vcc
	v_lshlrev_b32_e32 v90, 16, v89
	v_and_b32_e32 v91, 0xffff0000, v89
	v_ldexp_f32 v124, v43, v44
	v_add_u32_e32 v44, 17, v17
	v_cvt_f32_i32_e32 v44, v44
	v_mul_f32_e32 v43, v124, v18
	v_mul_f32_e32 v45, 0.15915494, v43
	v_floor_f32_e32 v45, v45
	v_fma_f32 v43, v43, 0.15915494, -v45
	v_mul_f32_e32 v45, 0xbed49a78, v44
	v_cmp_gt_f32_e32 vcc, s36, v45
	v_sin_f32_e32 v104, v43
	v_cos_f32_e32 v106, v43
	v_cndmask_b32_e32 v45, 0, v208, vcc
	v_fmac_f32_e32 v45, 0xbed49a78, v44
	v_exp_f32_e32 v44, v45
	v_cndmask_b32_e32 v43, 0, v209, vcc
	v_lshlrev_b32_e32 v178, 16, v92
	v_and_b32_e32 v179, 0xffff0000, v92
	v_ldexp_f32 v125, v44, v43
	v_add_u32_e32 v44, 18, v17
	v_cvt_f32_i32_e32 v44, v44
	v_mul_f32_e32 v43, v125, v18
	v_mul_f32_e32 v45, 0.15915494, v43
	v_floor_f32_e32 v45, v45
	v_fma_f32 v43, v43, 0.15915494, -v45
	v_mul_f32_e32 v45, 0xbed49a78, v44
	v_cmp_gt_f32_e32 vcc, s36, v45
	v_sin_f32_e32 v105, v43
	v_cos_f32_e32 v107, v43
	v_cndmask_b32_e32 v45, 0, v208, vcc
	v_fmac_f32_e32 v45, 0xbed49a78, v44
	v_exp_f32_e32 v44, v45
	v_cndmask_b32_e32 v43, 0, v209, vcc
	v_lshlrev_b32_e32 v92, 16, v88
	v_and_b32_e32 v93, 0xffff0000, v88
	v_ldexp_f32 v144, v44, v43
	v_add_u32_e32 v44, 19, v17
	v_cvt_f32_i32_e32 v44, v44
	v_mul_f32_e32 v43, v144, v18
	v_mul_f32_e32 v45, 0.15915494, v43
	v_floor_f32_e32 v45, v45
	v_fma_f32 v43, v43, 0.15915494, -v45
	v_mul_f32_e32 v45, 0xbed49a78, v44
	v_cmp_gt_f32_e32 vcc, s36, v45
	v_sin_f32_e32 v108, v43
	v_cos_f32_e32 v110, v43
	v_cndmask_b32_e32 v45, 0, v208, vcc
	v_fmac_f32_e32 v45, 0xbed49a78, v44
	v_exp_f32_e32 v44, v45
	v_cndmask_b32_e32 v43, 0, v209, vcc
	v_lshlrev_b32_e32 v184, 16, v87
	v_and_b32_e32 v185, 0xffff0000, v87
	v_ldexp_f32 v145, v44, v43
	v_add_u32_e32 v44, 20, v17
	v_cvt_f32_i32_e32 v44, v44
	v_mul_f32_e32 v43, v145, v18
	v_mul_f32_e32 v45, 0.15915494, v43
	v_floor_f32_e32 v45, v45
	v_fma_f32 v43, v43, 0.15915494, -v45
	v_mul_f32_e32 v45, 0xbed49a78, v44
	v_cmp_gt_f32_e32 vcc, s36, v45
	v_sin_f32_e32 v109, v43
	v_cos_f32_e32 v111, v43
	v_cndmask_b32_e32 v45, 0, v208, vcc
	v_fmac_f32_e32 v45, 0xbed49a78, v44
	v_exp_f32_e32 v44, v45
	v_cndmask_b32_e32 v43, 0, v209, vcc
	v_lshlrev_b32_e32 v88, 16, v83
	v_and_b32_e32 v89, 0xffff0000, v83
	v_ldexp_f32 v148, v44, v43
	v_add_u32_e32 v44, 21, v17
	v_lshlrev_b32_e32 v186, 16, v86
	v_and_b32_e32 v187, 0xffff0000, v86
	v_lshlrev_b32_e32 v86, 16, v82
	v_and_b32_e32 v87, 0xffff0000, v82
	v_lshlrev_b32_e32 v188, 16, v85
	v_and_b32_e32 v189, 0xffff0000, v85
	v_lshlrev_b32_e32 v82, 16, v81
	v_and_b32_e32 v83, 0xffff0000, v81
	v_lshlrev_b32_e32 v190, 16, v84
	v_and_b32_e32 v191, 0xffff0000, v84
	v_lshlrev_b32_e32 v84, 16, v80
	v_and_b32_e32 v85, 0xffff0000, v80
	v_lshlrev_b32_e32 v192, 16, v79
	v_and_b32_e32 v193, 0xffff0000, v79
	v_lshlrev_b32_e32 v80, 16, v75
	v_and_b32_e32 v81, 0xffff0000, v75
	v_lshlrev_b32_e32 v194, 16, v78
	v_and_b32_e32 v195, 0xffff0000, v78
	v_lshlrev_b32_e32 v78, 16, v74
	v_and_b32_e32 v79, 0xffff0000, v74
	v_lshlrev_b32_e32 v196, 16, v77
	v_and_b32_e32 v197, 0xffff0000, v77
	v_lshlrev_b32_e32 v74, 16, v73
	v_and_b32_e32 v75, 0xffff0000, v73
	v_lshlrev_b32_e32 v198, 16, v76
	v_and_b32_e32 v199, 0xffff0000, v76
	v_lshlrev_b32_e32 v76, 16, v72
	v_and_b32_e32 v77, 0xffff0000, v72
	v_lshlrev_b32_e32 v72, 16, v71
	v_and_b32_e32 v73, 0xffff0000, v71
	v_lshlrev_b32_e32 v214, 16, v67
	v_and_b32_e32 v215, 0xffff0000, v67
	v_lshlrev_b32_e32 v216, 16, v70
	v_and_b32_e32 v217, 0xffff0000, v70
	v_lshlrev_b32_e32 v70, 16, v66
	v_and_b32_e32 v71, 0xffff0000, v66
	v_lshlrev_b32_e32 v66, 16, v69
	v_and_b32_e32 v67, 0xffff0000, v69
	v_pk_fma_f32 v[68:69], v[222:223], v[222:223], v[68:69] op_sel_hi:[1,1,0]
	v_cvt_f32_i32_e32 v44, v44
	v_lshlrev_b32_e32 v220, 16, v65
	v_and_b32_e32 v221, 0xffff0000, v65
	v_lshlrev_b32_e32 v224, 16, v64
	v_and_b32_e32 v225, 0xffff0000, v64
	v_pk_fma_f32 v[64:65], v[66:67], v[66:67], v[68:69]
	v_mul_f32_e32 v68, v67, v67
	v_mul_f32_e32 v43, v148, v18
	v_pk_add_f32 v[64:65], v[68:69], v[64:65] op_sel_hi:[0,1]
	v_mul_f32_e32 v45, 0.15915494, v43
	v_pk_fma_f32 v[64:65], v[216:217], v[216:217], v[64:65]
	v_mul_f32_e32 v68, v217, v217
	v_floor_f32_e32 v45, v45
	v_pk_add_f32 v[64:65], v[68:69], v[64:65] op_sel_hi:[0,1]
	v_fma_f32 v43, v43, 0.15915494, -v45
	v_mul_f32_e32 v45, 0xbed49a78, v44
	v_pk_fma_f32 v[64:65], v[72:73], v[72:73], v[64:65]
	v_mul_f32_e32 v68, v73, v73
	v_cmp_gt_f32_e32 vcc, s36, v45
	v_pk_add_f32 v[64:65], v[68:69], v[64:65] op_sel_hi:[0,1]
	v_pk_fma_f32 v[64:65], v[198:199], v[198:199], v[64:65]
	v_cndmask_b32_e32 v45, 0, v208, vcc
; template <int NHQ, int NHKV>
; DI void attn_phase_l1(const u16* __restrict__ Q, const u16* __restrict__ K, const u16* __restrict__ Vt, u16* __restrict__ O, const float* __restrict__ qg, char* smem, const int wv) {
;     ...
;       float ssq = 0.f;
; #pragma unroll
;       for (int i = 0; i < NS; ++i) {
;         qf[i] = *(const bf16x8*)(qrow + 16 * i);
;         float t8[8]; unpack8(__builtin_bit_cast(u32x4, qf[i]), t8);
; #pragma unroll
;         for (int e = 0; e < 8; ++e) ssq += t8[e] * t8[e];
;       }
;       ssq = xhalf_sum(ssq);
;       const float rn = rsqrtf(ssq * (1.f / DQK) + EPS) * (0.08838834764831845f * 1.4426950408889634f);
;     ...
;       const float prow = (float)((pq - NMETA) >> 6), pcol = (float)((pq - NMETA) & 63);
;       A_QROPE(0, 2, 0, prow); A_QROPE(1, 3, 1, prow);
;       A_QROPE(4, 6, 0, pcol); A_QROPE(5, 7, 1, pcol);
	v_mul_f32_e32 v68, v199, v199
	v_fmac_f32_e32 v45, 0xbed49a78, v44
	v_pk_add_f32 v[64:65], v[68:69], v[64:65] op_sel_hi:[0,1]
	v_exp_f32_e32 v44, v45
	v_pk_fma_f32 v[64:65], v[196:197], v[196:197], v[64:65]
	v_mul_f32_e32 v68, v197, v197
	v_pk_add_f32 v[64:65], v[68:69], v[64:65] op_sel_hi:[0,1]
	v_pk_fma_f32 v[64:65], v[194:195], v[194:195], v[64:65]
	v_mul_f32_e32 v68, v195, v195
	v_sin_f32_e32 v112, v43
	v_cos_f32_e32 v114, v43
	v_cndmask_b32_e32 v43, 0, v209, vcc
	v_pk_add_f32 v[64:65], v[68:69], v[64:65] op_sel_hi:[0,1]
	v_ldexp_f32 v149, v44, v43
	v_add_u32_e32 v44, 22, v17
	v_pk_fma_f32 v[64:65], v[192:193], v[192:193], v[64:65]
	v_mul_f32_e32 v68, v193, v193
	v_cvt_f32_i32_e32 v44, v44
	v_pk_add_f32 v[64:65], v[68:69], v[64:65] op_sel_hi:[0,1]
	v_mul_f32_e32 v43, v149, v18
	v_pk_fma_f32 v[64:65], v[224:225], v[224:225], v[64:65]
	v_mul_f32_e32 v68, v225, v225
	v_mul_f32_e32 v45, 0.15915494, v43
	v_pk_add_f32 v[64:65], v[68:69], v[64:65] op_sel_hi:[0,1]
	v_floor_f32_e32 v45, v45
	v_pk_fma_f32 v[64:65], v[220:221], v[220:221], v[64:65]
	v_mul_f32_e32 v68, v221, v221
	v_fma_f32 v43, v43, 0.15915494, -v45
	v_mul_f32_e32 v45, 0xbed49a78, v44
	v_pk_add_f32 v[64:65], v[68:69], v[64:65] op_sel_hi:[0,1]
	v_cmp_gt_f32_e32 vcc, s36, v45
	v_pk_fma_f32 v[64:65], v[70:71], v[70:71], v[64:65]
	v_mul_f32_e32 v68, v71, v71
	v_cndmask_b32_e32 v45, 0, v208, vcc
	v_pk_add_f32 v[64:65], v[68:69], v[64:65] op_sel_hi:[0,1]
	v_fmac_f32_e32 v45, 0xbed49a78, v44
	v_pk_fma_f32 v[64:65], v[214:215], v[214:215], v[64:65]
	v_mul_f32_e32 v68, v215, v215
	v_exp_f32_e32 v44, v45
	v_pk_add_f32 v[64:65], v[68:69], v[64:65] op_sel_hi:[0,1]
	v_pk_fma_f32 v[64:65], v[76:77], v[76:77], v[64:65]
	v_mul_f32_e32 v68, v77, v77
	v_pk_add_f32 v[64:65], v[68:69], v[64:65] op_sel_hi:[0,1]
	v_sin_f32_e32 v113, v43
	v_cos_f32_e32 v115, v43
	v_cndmask_b32_e32 v43, 0, v209, vcc
	v_add_u32_e32 v17, 23, v17
	v_pk_fma_f32 v[64:65], v[74:75], v[74:75], v[64:65]
	v_mul_f32_e32 v68, v75, v75
	v_ldexp_f32 v152, v44, v43
	v_cvt_f32_i32_e32 v17, v17
	v_pk_add_f32 v[64:65], v[68:69], v[64:65] op_sel_hi:[0,1]
	v_mul_f32_e32 v43, v152, v18
	v_pk_fma_f32 v[64:65], v[78:79], v[78:79], v[64:65]
	v_mul_f32_e32 v68, v79, v79
	v_mul_f32_e32 v44, 0.15915494, v43
	v_pk_add_f32 v[64:65], v[68:69], v[64:65] op_sel_hi:[0,1]
	v_floor_f32_e32 v44, v44
	v_pk_fma_f32 v[64:65], v[80:81], v[80:81], v[64:65]
	v_mul_f32_e32 v68, v81, v81
	v_fma_f32 v43, v43, 0.15915494, -v44
	v_mul_f32_e32 v44, 0xbed49a78, v17
	v_pk_add_f32 v[64:65], v[68:69], v[64:65] op_sel_hi:[0,1]
	v_cmp_gt_f32_e32 vcc, s36, v44
	v_pk_fma_f32 v[64:65], v[190:191], v[190:191], v[64:65]
	v_mul_f32_e32 v68, v191, v191
	v_cndmask_b32_e32 v44, 0, v208, vcc
	v_pk_add_f32 v[64:65], v[68:69], v[64:65] op_sel_hi:[0,1]
	v_fmac_f32_e32 v44, 0xbed49a78, v17
	v_pk_fma_f32 v[64:65], v[188:189], v[188:189], v[64:65]
	v_mul_f32_e32 v68, v189, v189
	v_exp_f32_e32 v17, v44
	v_pk_add_f32 v[64:65], v[68:69], v[64:65] op_sel_hi:[0,1]
	v_pk_fma_f32 v[64:65], v[186:187], v[186:187], v[64:65]
	v_mul_f32_e32 v68, v187, v187
	v_pk_add_f32 v[64:65], v[68:69], v[64:65] op_sel_hi:[0,1]
	v_sin_f32_e32 v132, v43
	v_cos_f32_e32 v134, v43
	v_cndmask_b32_e32 v43, 0, v209, vcc
	v_pk_fma_f32 v[64:65], v[184:185], v[184:185], v[64:65]
	v_mul_f32_e32 v68, v185, v185
	v_ldexp_f32 v153, v17, v43
	v_pk_add_f32 v[64:65], v[68:69], v[64:65] op_sel_hi:[0,1]
	v_mul_f32_e32 v17, v153, v18
	v_pk_fma_f32 v[64:65], v[178:179], v[178:179], v[64:65]
	v_mul_f32_e32 v68, v179, v179
	v_mul_f32_e32 v18, 0.15915494, v17
	v_pk_add_f32 v[64:65], v[68:69], v[64:65] op_sel_hi:[0,1]
	v_floor_f32_e32 v18, v18
	v_pk_fma_f32 v[64:65], v[176:177], v[176:177], v[64:65]
	v_mul_f32_e32 v68, v177, v177
	v_fma_f32 v17, v17, 0.15915494, -v18
	v_pk_add_f32 v[64:65], v[68:69], v[64:65] op_sel_hi:[0,1]
	v_sin_f32_e32 v133, v17
	v_cos_f32_e32 v135, v17
	v_mul_f32_e32 v17, 0.15915494, v16
	v_pk_fma_f32 v[64:65], v[174:175], v[174:175], v[64:65]
	v_mul_f32_e32 v68, v175, v175
	v_floor_f32_e32 v17, v17
	v_pk_add_f32 v[64:65], v[68:69], v[64:65] op_sel_hi:[0,1]
	v_fma_f32 v16, v16, 0.15915494, -v17
	v_pk_fma_f32 v[64:65], v[158:159], v[158:159], v[64:65]
	v_mul_f32_e32 v68, v159, v159
	v_sin_f32_e32 v120, v16
	v_cos_f32_e32 v122, v16
	v_mul_f32_e32 v16, v20, v155
	v_pk_add_f32 v[64:65], v[68:69], v[64:65] op_sel_hi:[0,1]
	v_mul_f32_e32 v17, 0.15915494, v16
	v_pk_fma_f32 v[64:65], v[84:85], v[84:85], v[64:65]
	v_mul_f32_e32 v68, v85, v85
	v_floor_f32_e32 v17, v17
	v_pk_add_f32 v[64:65], v[68:69], v[64:65] op_sel_hi:[0,1]
	v_fma_f32 v16, v16, 0.15915494, -v17
	v_pk_fma_f32 v[64:65], v[82:83], v[82:83], v[64:65]
	v_mul_f32_e32 v68, v83, v83
	v_sin_f32_e32 v121, v16
	v_cos_f32_e32 v123, v16
	v_mul_f32_e32 v16, v21, v155
	v_pk_add_f32 v[64:65], v[68:69], v[64:65] op_sel_hi:[0,1]
	v_mul_f32_e32 v17, 0.15915494, v16
	v_pk_fma_f32 v[64:65], v[86:87], v[86:87], v[64:65]
	v_mul_f32_e32 v68, v87, v87
	v_floor_f32_e32 v17, v17
	v_pk_add_f32 v[64:65], v[68:69], v[64:65] op_sel_hi:[0,1]
	v_fma_f32 v16, v16, 0.15915494, -v17
	v_pk_fma_f32 v[64:65], v[88:89], v[88:89], v[64:65]
	v_mul_f32_e32 v68, v89, v89
	v_sin_f32_e32 v128, v16
	v_cos_f32_e32 v130, v16
	v_mul_f32_e32 v16, v22, v155
	v_pk_add_f32 v[64:65], v[68:69], v[64:65] op_sel_hi:[0,1]
	v_mul_f32_e32 v17, 0.15915494, v16
	v_pk_fma_f32 v[64:65], v[92:93], v[92:93], v[64:65]
	v_mul_f32_e32 v68, v93, v93
	v_floor_f32_e32 v17, v17
	v_pk_add_f32 v[64:65], v[68:69], v[64:65] op_sel_hi:[0,1]
	v_fma_f32 v16, v16, 0.15915494, -v17
	v_pk_fma_f32 v[64:65], v[90:91], v[90:91], v[64:65]
	v_mul_f32_e32 v68, v91, v91
	v_sin_f32_e32 v129, v16
	v_cos_f32_e32 v131, v16
	v_mul_f32_e32 v16, v23, v155
; #define B_LOADK(Kb_, tile_) do { const char* kp_ = (const char*)(Kb_) + (size_t)(tile_) * (64 * LDK * 2); const unsigned ko_ = ((tile_) == NT - 1) ? koffL : koff; \
;     _Pragma("unroll") for (int i_ = 0; i_ < NKC; ++i_) rk[i_] = *(const u32x4*)(kp_ + ko_ + i_ * 128); } while (0)
; #define B_LOADV(Vb_, tile_) do { const char* vp_ = (const char*)(Vb_) + (size_t)(tile_) * 128; \
;     rv[0] = *(const u32x4*)(vp_ + voff); rv[1] = *(const u32x4*)(vp_ + voff + 64 * LP * 2); } while (0)
; #define B_WRITEK(bi_) do { char* b_w = kb0 + (bi_) * KBYTES + kwoff; \
;     _Pragma("unroll") for (int i_ = 0; i_ < NKC; ++i_) *(u32x4*)(b_w + i_ * 128) = rk[i_]; } while (0)
; #define B_WRITEV(bi_) do { char* b_w = vb0 + (bi_) * VBYTES + vwoff; \
;     *(u32x4*)(b_w) = rv[0]; *(u32x4*)(b_w + 64 * VSTR) = rv[1]; } while (0)
; template <int NHQ, int NHKV>
; DI void attn_phase_l1(const u16* __restrict__ Q, const u16* __restrict__ K, const u16* __restrict__ Vt, u16* __restrict__ O, const float* __restrict__ qg, char* smem, const int wv) {
;     ...
;       ssq = xhalf_sum(ssq);
;       const float rn = rsqrtf(ssq * (1.f / DQK) + EPS) * (0.08838834764831845f * 1.4426950408889634f);
;     ...
;       const float prow = (float)((pq - NMETA) >> 6), pcol = (float)((pq - NMETA) & 63);
;       A_QROPE(0, 2, 0, prow); A_QROPE(1, 3, 1, prow);
;       A_QROPE(4, 6, 0, pcol); A_QROPE(5, 7, 1, pcol);
;     ...
;     }
;     float l = 0.f;
; #pragma unroll
;     for (int d = 0; d < 4; ++d)
; #pragma unroll
;       for (int i = 0; i < 16; ++i) o[d][i] = 0.f;
;     __syncthreads();
;     B_LOADK(Kb, 0); B_WRITEK(0); B_LOADK(Kb, 1); B_WRITEK(1); B_LOADV(Vb, 0); B_WRITEV(0);
;     B_LOADK(Kb, 2); B_LOADV(Vb, 1);
	v_pk_add_f32 v[64:65], v[68:69], v[64:65] op_sel_hi:[0,1]
	v_mul_f32_e32 v17, 0.15915494, v16
	v_pk_fma_f32 v[64:65], v[94:95], v[94:95], v[64:65]
	v_mul_f32_e32 v68, v95, v95
	v_floor_f32_e32 v17, v17
	v_pk_add_f32 v[64:65], v[68:69], v[64:65] op_sel_hi:[0,1]
	v_fma_f32 v16, v16, 0.15915494, -v17
	v_pk_fma_f32 v[64:65], v[156:157], v[156:157], v[64:65]
	v_mul_f32_e32 v68, v157, v157
	v_sin_f32_e32 v136, v16
	v_cos_f32_e32 v138, v16
	v_mul_f32_e32 v16, v40, v155
	v_pk_add_f32 v[64:65], v[68:69], v[64:65] op_sel_hi:[0,1]
	v_mul_f32_e32 v17, 0.15915494, v16
	v_mov_b32_e32 v65, v64
	v_floor_f32_e32 v17, v17
	s_nop 0
	v_permlane32_swap_b32_e32 v64, v65
	v_fma_f32 v16, v16, 0.15915494, -v17
	v_add_f32_e32 v64, v64, v65
	v_sin_f32_e32 v137, v16
	v_cos_f32_e32 v139, v16
	v_mul_f32_e32 v16, v41, v155
	v_fmamk_f32 v64, v64, 0x3c000000, v210
	v_mul_f32_e32 v17, 0.15915494, v16
	v_mul_f32_e32 v65, 0x4b800000, v64
	v_cmp_gt_f32_e32 vcc, s37, v64
	v_floor_f32_e32 v17, v17
	v_fma_f32 v16, v16, 0.15915494, -v17
	v_cndmask_b32_e32 v64, v64, v65, vcc
	v_mul_f32_e32 v153, v153, v155
	v_rsq_f32_e32 v64, v64
	v_sin_f32_e32 v116, v16
	v_cos_f32_e32 v118, v16
	v_mul_f32_e32 v16, v42, v155
	v_mul_f32_e32 v124, v124, v155
	v_mul_f32_e32 v125, v125, v155
	v_mul_f32_e32 v144, v144, v155
	v_mul_f32_e32 v145, v145, v155
	v_mul_f32_e32 v148, v148, v155
	v_mul_f32_e32 v149, v149, v155
	v_mul_f32_e32 v152, v152, v155
	v_mul_f32_e32 v155, 0.15915494, v153
	v_floor_f32_e32 v155, v155
	v_fma_f32 v65, v153, 0.15915494, -v155
	v_sin_f32_e32 v153, v65
	v_cos_f32_e32 v155, v65
	v_mul_f32_e32 v65, 0x45800000, v64
	v_cndmask_b32_e32 v64, v64, v65, vcc
	v_sin_f32_e32 v181, v0
	v_cos_f32_e32 v183, v0
	global_load_dwordx4 v[8:11], v[166:167], off offset:64
	global_load_dwordx4 v[0:3], v[166:167], off offset:80
	v_mul_f32_e32 v64, 0x3e0293ee, v64
	global_load_dwordx4 v[12:15], v[166:167], off offset:192
	global_load_dwordx4 v[4:7], v[166:167], off offset:208
	s_waitcnt vmcnt(7)
	v_pk_mul_f32 v[28:29], v[28:29], v[64:65] op_sel_hi:[1,0]
	v_pk_mul_f32 v[30:31], v[30:31], v[64:65] op_sel_hi:[1,0]
	v_pk_mul_f32 v[28:29], v[28:29], v[222:223]
	s_waitcnt vmcnt(5)
	v_pk_mul_f32 v[36:37], v[36:37], v[64:65] op_sel_hi:[1,0]
	v_pk_mul_f32 v[30:31], v[30:31], v[66:67]
	v_pk_mul_f32 v[36:37], v[36:37], v[224:225]
	v_pk_mul_f32 v[66:67], v[96:97], v[28:29]
	v_pk_mul_f32 v[38:39], v[38:39], v[64:65] op_sel_hi:[1,0]
	v_pk_fma_f32 v[66:67], v[98:99], v[36:37], v[66:67]
	v_pk_mul_f32 v[36:37], v[96:97], v[36:37]
	v_pk_mul_f32 v[24:25], v[24:25], v[64:65] op_sel_hi:[1,0]
	v_pk_mul_f32 v[38:39], v[38:39], v[220:221]
	v_pk_fma_f32 v[28:29], v[98:99], v[28:29], v[36:37] neg_lo:[0,0,1] neg_hi:[0,0,1]
	v_pk_mul_f32 v[36:37], v[100:101], v[30:31]
	v_pk_mul_f32 v[24:25], v[24:25], v[216:217]
	s_waitcnt vmcnt(4)
	v_pk_mul_f32 v[32:33], v[32:33], v[64:65] op_sel_hi:[1,0]
	v_pk_fma_f32 v[36:37], v[102:103], v[38:39], v[36:37]
	v_pk_mul_f32 v[38:39], v[100:101], v[38:39]
	v_pk_mul_f32 v[26:27], v[26:27], v[64:65] op_sel_hi:[1,0]
	v_pk_mul_f32 v[32:33], v[32:33], v[70:71]
	v_pk_fma_f32 v[30:31], v[102:103], v[30:31], v[38:39] neg_lo:[0,0,1] neg_hi:[0,0,1]
	v_pk_mul_f32 v[38:39], v[140:141], v[24:25]
	s_add_u32 s24, s24, s22
	global_load_dwordx4 v[60:63], v[166:167], off offset:256
	global_load_dwordx4 v[56:59], v[166:167], off offset:272
	global_load_dwordx4 v[52:55], v[166:167], off offset:384
	global_load_dwordx4 v[48:51], v[166:167], off offset:400
	v_pk_mul_f32 v[26:27], v[26:27], v[72:73]
	v_pk_mul_f32 v[34:35], v[34:35], v[64:65] op_sel_hi:[1,0]
	v_pk_fma_f32 v[98:99], v[142:143], v[32:33], v[38:39]
	v_pk_mul_f32 v[32:33], v[140:141], v[32:33]
	s_mul_i32 s26, s42, 0x2080
	s_addc_u32 s25, s25, s23
	v_pk_mul_f32 v[34:35], v[34:35], v[214:215]
	v_pk_fma_f32 v[24:25], v[142:143], v[24:25], v[32:33] neg_lo:[0,0,1] neg_hi:[0,0,1]
	v_pk_mul_f32 v[32:33], v[180:181], v[26:27]
	s_mul_hi_i32 s27, s42, 0x2080
	s_add_u32 s26, s31, s26
	v_pk_fma_f32 v[140:141], v[182:183], v[34:35], v[32:33]
	v_pk_mul_f32 v[32:33], v[180:181], v[34:35]
	v_lshl_add_u64 v[180:181], s[24:25], 0, v[160:161]
	s_addc_u32 s27, s34, s27
	v_pk_fma_f32 v[26:27], v[182:183], v[26:27], v[32:33] neg_lo:[0,0,1] neg_hi:[0,0,1]
	v_add_co_u32_e32 v32, vcc, s38, v180
	v_mul_f32_e32 v17, 0.15915494, v16
	s_nop 0
	v_addc_co_u32_e32 v33, vcc, 0, v181, vcc
	v_lshl_add_u64 v[142:143], s[26:27], 0, v[162:163]
	v_floor_f32_e32 v17, v17
	v_add_co_u32_e32 v182, vcc, s39, v142
	v_fma_f32 v16, v16, 0.15915494, -v17
	v_cvt_pk_bf16_f32 v97, v36, v37
	v_lshl_add_u64 v[36:37], v[180:181], 0, s[8:9]
	v_addc_co_u32_e32 v183, vcc, 0, v143, vcc
	v_sin_f32_e32 v117, v16
	v_cos_f32_e32 v119, v16
	global_load_dwordx4 v[44:47], v[166:167], off offset:320
	global_load_dwordx4 v[40:43], v[166:167], off offset:336
	global_load_dwordx4 v[20:23], v[166:167], off offset:448
	global_load_dwordx4 v[16:19], v[166:167], off offset:464
	v_cvt_pk_bf16_f32 v100, v28, v29
	v_cvt_pk_bf16_f32 v101, v30, v31
	v_cvt_pk_bf16_f32 v102, v24, v25
	v_cvt_pk_bf16_f32 v103, v26, v27
	v_cvt_pk_bf16_f32 v96, v66, v67
	s_barrier
; #define B_LOADK(Kb_, tile_) do { const char* kp_ = (const char*)(Kb_) + (size_t)(tile_) * (64 * LDK * 2); const unsigned ko_ = ((tile_) == NT - 1) ? koffL : koff; \
;     _Pragma("unroll") for (int i_ = 0; i_ < NKC; ++i_) rk[i_] = *(const u32x4*)(kp_ + ko_ + i_ * 128); } while (0)
; #define B_LOADV(Vb_, tile_) do { const char* vp_ = (const char*)(Vb_) + (size_t)(tile_) * 128; \
;     rv[0] = *(const u32x4*)(vp_ + voff); rv[1] = *(const u32x4*)(vp_ + voff + 64 * LP * 2); } while (0)
; #define B_WRITEK(bi_) do { char* b_w = kb0 + (bi_) * KBYTES + kwoff; \
;     _Pragma("unroll") for (int i_ = 0; i_ < NKC; ++i_) *(u32x4*)(b_w + i_ * 128) = rk[i_]; } while (0)
; #define B_WRITEV(bi_) do { char* b_w = vb0 + (bi_) * VBYTES + vwoff; \
;     *(u32x4*)(b_w) = rv[0]; *(u32x4*)(b_w + 64 * VSTR) = rv[1]; } while (0)
; template <int NHQ, int NHKV>
; DI void attn_phase_l1(const u16* __restrict__ Q, const u16* __restrict__ K, const u16* __restrict__ Vt, u16* __restrict__ O, const float* __restrict__ qg, char* smem, const int wv) {
;     ...
;       const float prow = (float)((pq - NMETA) >> 6), pcol = (float)((pq - NMETA) & 63);
;       A_QROPE(0, 2, 0, prow); A_QROPE(1, 3, 1, prow);
;       A_QROPE(4, 6, 0, pcol); A_QROPE(5, 7, 1, pcol);
;     ...
;     __syncthreads();
;     B_LOADK(Kb, 0); B_WRITEK(0); B_LOADK(Kb, 1); B_WRITEK(1); B_LOADV(Vb, 0); B_WRITEV(0);
;     B_LOADK(Kb, 2); B_LOADV(Vb, 1);
;     __syncthreads();
	global_load_dwordx4 v[24:27], v[180:181], off
	global_load_dwordx4 v[28:31], v[180:181], off offset:128
	s_nop 0
	global_load_dwordx4 v[32:35], v[32:33], off
	s_nop 0
	global_load_dwordx4 v[36:39], v[36:37], off offset:128
	v_cvt_pk_bf16_f32 v98, v98, v99
	global_load_dwordx4 v[66:69], v[142:143], off
	global_load_dwordx4 v[70:73], v[182:183], off
	s_waitcnt vmcnt(5)
	ds_write_b128 v203, v[24:27]
	s_waitcnt vmcnt(4)
	ds_write_b128 v203, v[28:31] offset:128
	s_waitcnt vmcnt(3)
	ds_write_b128 v203, v[32:35] offset:17408
	s_waitcnt vmcnt(2)
	ds_write_b128 v203, v[36:39] offset:17536
	v_pk_mul_f32 v[8:9], v[8:9], v[64:65] op_sel_hi:[1,0]
	v_pk_mul_f32 v[12:13], v[12:13], v[64:65] op_sel_hi:[1,0]
	v_pk_mul_f32 v[8:9], v[8:9], v[198:199]
	v_pk_mul_f32 v[14:15], v[14:15], v[64:65] op_sel_hi:[1,0]
	v_pk_mul_f32 v[10:11], v[10:11], v[64:65] op_sel_hi:[1,0]
	v_pk_mul_f32 v[12:13], v[12:13], v[76:77]
	v_pk_mul_f32 v[14:15], v[14:15], v[74:75]
	v_pk_mul_f32 v[74:75], v[104:105], v[8:9]
	v_pk_mul_f32 v[10:11], v[10:11], v[196:197]
	v_pk_fma_f32 v[74:75], v[106:107], v[12:13], v[74:75]
	v_pk_mul_f32 v[12:13], v[104:105], v[12:13]
	v_pk_mul_f32 v[0:1], v[0:1], v[64:65] op_sel_hi:[1,0]
	v_pk_fma_f32 v[8:9], v[106:107], v[8:9], v[12:13] neg_lo:[0,0,1] neg_hi:[0,0,1]
	v_pk_mul_f32 v[12:13], v[108:109], v[10:11]
	v_pk_mul_f32 v[0:1], v[0:1], v[194:195]
	v_pk_mul_f32 v[4:5], v[4:5], v[64:65] op_sel_hi:[1,0]
	v_pk_fma_f32 v[12:13], v[110:111], v[14:15], v[12:13]
	v_pk_mul_f32 v[14:15], v[108:109], v[14:15]
	v_pk_mul_f32 v[2:3], v[2:3], v[64:65] op_sel_hi:[1,0]
	v_pk_mul_f32 v[4:5], v[4:5], v[78:79]
	v_pk_fma_f32 v[10:11], v[110:111], v[10:11], v[14:15] neg_lo:[0,0,1] neg_hi:[0,0,1]
	v_pk_mul_f32 v[14:15], v[112:113], v[0:1]
	v_pk_mul_f32 v[2:3], v[2:3], v[192:193]
	v_pk_mul_f32 v[6:7], v[6:7], v[64:65] op_sel_hi:[1,0]
	v_pk_fma_f32 v[14:15], v[114:115], v[4:5], v[14:15]
	v_pk_mul_f32 v[4:5], v[112:113], v[4:5]
	v_pk_mul_f32 v[6:7], v[6:7], v[80:81]
	v_pk_fma_f32 v[0:1], v[114:115], v[0:1], v[4:5] neg_lo:[0,0,1] neg_hi:[0,0,1]
	v_pk_mul_f32 v[4:5], v[132:133], v[2:3]
	v_cvt_pk_bf16_f32 v108, v8, v9
	v_pk_mul_f32 v[8:9], v[64:65], v[52:53] op_sel_hi:[0,1]
	v_pk_fma_f32 v[4:5], v[134:135], v[6:7], v[4:5]
	v_cvt_pk_bf16_f32 v110, v0, v1
	v_cvt_pk_bf16_f32 v105, v12, v13
	v_pk_mul_f32 v[0:1], v[60:61], v[64:65] op_sel_hi:[1,0]
	v_pk_mul_f32 v[8:9], v[8:9], v[84:85]
	v_pk_mul_f32 v[12:13], v[64:65], v[54:55] op_sel_hi:[0,1]
	v_pk_mul_f32 v[6:7], v[132:133], v[6:7]
	v_cvt_pk_bf16_f32 v109, v10, v11
	v_cvt_pk_bf16_f32 v107, v4, v5
	v_pk_mul_f32 v[0:1], v[0:1], v[190:191]
	v_pk_mul_f32 v[4:5], v[62:63], v[64:65] op_sel_hi:[1,0]
	v_pk_mul_f32 v[10:11], v[64:65], v[48:49] op_sel_hi:[0,1]
	v_pk_mul_f32 v[12:13], v[12:13], v[82:83]
	v_pk_mul_f32 v[48:49], v[120:121], v[8:9]
	v_pk_mul_f32 v[8:9], v[122:123], v[8:9]
	v_pk_fma_f32 v[2:3], v[134:135], v[2:3], v[6:7] neg_lo:[0,0,1] neg_hi:[0,0,1]
	v_pk_mul_f32 v[4:5], v[4:5], v[188:189]
	v_pk_fma_f32 v[48:49], v[122:123], v[0:1], v[48:49] neg_lo:[0,0,1] neg_hi:[0,0,1]
	v_pk_fma_f32 v[8:9], v[120:121], v[0:1], v[8:9]
	v_pk_mul_f32 v[0:1], v[128:129], v[12:13]
	v_cvt_pk_bf16_f32 v111, v2, v3
	v_cvt_pk_bf16_f32 v106, v14, v15
	v_pk_mul_f32 v[2:3], v[64:65], v[56:57] op_sel_hi:[0,1]
	v_pk_mul_f32 v[10:11], v[10:11], v[86:87]
	v_pk_mul_f32 v[14:15], v[64:65], v[50:51] op_sel_hi:[0,1]
	v_pk_fma_f32 v[50:51], v[130:131], v[4:5], v[0:1] neg_lo:[0,0,1] neg_hi:[0,0,1]
	v_pk_mul_f32 v[0:1], v[130:131], v[12:13]
	v_pk_mul_f32 v[2:3], v[2:3], v[186:187]
	v_pk_fma_f32 v[52:53], v[128:129], v[4:5], v[0:1]
	v_pk_mul_f32 v[0:1], v[136:137], v[10:11]
	v_pk_mul_f32 v[6:7], v[64:65], v[58:59] op_sel_hi:[0,1]
	v_pk_mul_f32 v[14:15], v[14:15], v[88:89]
	v_pk_fma_f32 v[4:5], v[138:139], v[2:3], v[0:1] neg_lo:[0,0,1] neg_hi:[0,0,1]
	v_pk_mul_f32 v[0:1], v[138:139], v[10:11]
	v_pk_mul_f32 v[6:7], v[6:7], v[184:185]
	v_pk_fma_f32 v[54:55], v[136:137], v[2:3], v[0:1]
	v_pk_mul_f32 v[0:1], v[116:117], v[14:15]
	v_add_co_u32_e32 v2, vcc, s40, v180
	v_pk_fma_f32 v[10:11], v[118:119], v[6:7], v[0:1] neg_lo:[0,0,1] neg_hi:[0,0,1]
	s_waitcnt vmcnt(1)
	ds_write_b128 v204, v[66:69] offset:34816
	s_waitcnt vmcnt(0)
	ds_write_b128 v204, v[70:73] offset:44032
	v_lshl_add_u64 v[0:1], v[180:181], 0, s[14:15]
	v_addc_co_u32_e32 v3, vcc, 0, v181, vcc
	v_cvt_pk_bf16_f32 v99, v140, v141
	global_load_dwordx4 v[136:139], v[142:143], off offset:128
	v_pk_mul_f32 v[12:13], v[118:119], v[14:15]
	global_load_dwordx4 v[140:143], v[182:183], off offset:128
	global_load_dwordx4 v[128:131], v[2:3], off
	global_load_dwordx4 v[132:135], v[0:1], off offset:128
	s_waitcnt lgkmcnt(0)
	s_barrier
; DI unsigned cvtpk(float lo, float hi) { f32x2 v = {lo, hi}; return __builtin_bit_cast(unsigned, __builtin_convertvector(v, bf16x2_t)); }
; template <int NHQ, int NHKV>
; DI void attn_phase_l1(const u16* __restrict__ Q, const u16* __restrict__ K, const u16* __restrict__ Vt, u16* __restrict__ O, const float* __restrict__ qg, char* smem, const int wv) {
;     ...
;       const float prow = (float)((pq - NMETA) >> 6), pcol = (float)((pq - NMETA) & 63);
;       A_QROPE(0, 2, 0, prow); A_QROPE(1, 3, 1, prow);
;       A_QROPE(4, 6, 0, pcol); A_QROPE(5, 7, 1, pcol);
;     ...
;     {
;       const char* sk = kb0 + r32 * KSTR + hh * 16;
; #pragma unroll
;       for (int i = 0; i < 16; ++i) { s0[i] = 0.f; s1[i] = 0.f; }
; #pragma unroll
;       for (int i = 0; i < NS; ++i) {
;         const bf16x8 k0f = *(const bf16x8*)(sk + i * 32), k1f = *(const bf16x8*)(sk + 32 * KSTR + i * 32);
;         s0 = __builtin_amdgcn_mfma_f32_32x32x16_bf16(k0f, qf[i], s0, 0, 0, 0);
;         s1 = __builtin_amdgcn_mfma_f32_32x32x16_bf16(k1f, qf[i], s1, 0, 0, 0);
;       }
;       unsigned w_[16]; f32x2 ps2 = {0.f, 0.f};
; #pragma unroll
;       for (int i = 0; i < 8; ++i) { f32x2 v; v[0] = __builtin_amdgcn_exp2f(s0[2 * i]); v[1] = __builtin_amdgcn_exp2f(s0[2 * i + 1]); ps2 += v; w_[i] = cvtpk(v[0], v[1]); }
; #pragma unroll
;       for (int i = 0; i < 8; ++i) { f32x2 v; v[0] = __builtin_amdgcn_exp2f(s1[2 * i]); v[1] = __builtin_amdgcn_exp2f(s1[2 * i + 1]); ps2 += v; w_[8 + i] = cvtpk(v[0], v[1]); }
;       l += ps2[0] + ps2[1];
; #pragma unroll
;       for (int q = 0; q < 4; ++q) pb[q] = __builtin_bit_cast(bf16x8, u32x4{w_[4 * q], w_[4 * q + 1], w_[4 * q + 2], w_[4 * q + 3]});
;     }
	ds_read_b128 v[0:3], v205
	ds_read_b128 v[24:27], v205 offset:32
	v_pk_fma_f32 v[32:33], v[116:117], v[6:7], v[12:13]
	v_cvt_pk_bf16_f32 v118, v4, v5
	v_cvt_pk_bf16_f32 v119, v10, v11
	v_cvt_pk_bf16_f32 v112, v8, v9
	s_waitcnt lgkmcnt(1)
	v_mfma_f32_32x32x16_bf16 v[0:15], v[0:3], v[100:103], 0
	v_mul_f32_e64 v28, v64, v44
	v_mul_f32_e64 v29, v64, v45
	v_mul_f32_e64 v34, v28, v178
	v_mul_f32_e64 v35, v29, v179
	v_mul_f32_e64 v28, v64, v40
	v_mul_f32_e64 v29, v64, v41
	v_pk_mul_f32 v[36:37], v[28:29], v[174:175]
	ds_read_b128 v[28:31], v205 offset:64
	v_pk_mul_f32 v[16:17], v[64:65], v[16:17] op_sel_hi:[0,1]
	v_mul_f32_e32 v126, 0.15915494, v124
	s_waitcnt lgkmcnt(1)
	v_mfma_f32_32x32x16_bf16 v[0:15], v[24:27], v[108:111], v[0:15]
	v_mul_f32_e64 v24, v64, v46
	v_mul_f32_e64 v25, v64, v47
	v_mul_f32_e64 v38, v24, v176
	v_mul_f32_e64 v39, v25, v177
	v_mul_f32_e64 v24, v64, v42
	v_mul_f32_e64 v25, v64, v43
	v_pk_mul_f32 v[40:41], v[24:25], v[158:159]
	ds_read_b128 v[24:27], v205 offset:96
	v_mul_f32_e32 v127, 0.15915494, v125
	v_floor_f32_e32 v126, v126
	s_waitcnt lgkmcnt(1)
	v_mfma_f32_32x32x16_bf16 v[0:15], v[28:31], v[96:99], v[0:15]
	v_mul_f32_e64 v28, v16, v94
	v_mul_f32_e64 v29, v17, v95
	v_mul_f32_e64 v16, v64, v22
	v_mul_f32_e64 v17, v64, v23
	v_floor_f32_e32 v127, v127
	v_mul_f32_e32 v146, 0.15915494, v144
	v_mul_f32_e32 v147, 0.15915494, v145
	v_pk_mul_f32 v[30:31], v[16:17], v[90:91]
	v_pk_mul_f32 v[16:17], v[64:65], v[18:19] op_sel_hi:[0,1]
	v_fma_f32 v126, v124, 0.15915494, -v126
	v_fma_f32 v127, v125, 0.15915494, -v127
	v_floor_f32_e32 v146, v146
	v_floor_f32_e32 v147, v147
	v_mul_f32_e32 v150, 0.15915494, v148
	v_mul_f32_e32 v151, 0.15915494, v149
	v_cvt_pk_bf16_f32 v104, v74, v75
	v_pk_mul_f32 v[44:45], v[16:17], v[156:157]
	ds_read_b128 v[16:19], v205 offset:128
	v_sin_f32_e32 v124, v126
	v_sin_f32_e32 v125, v127
	v_fma_f32 v146, v144, 0.15915494, -v146
	v_fma_f32 v147, v145, 0.15915494, -v147
	v_floor_f32_e32 v150, v150
	v_floor_f32_e32 v151, v151
	s_waitcnt lgkmcnt(1)
	v_mfma_f32_32x32x16_bf16 v[0:15], v[24:27], v[104:107], v[0:15]
	v_cos_f32_e32 v126, v126
	v_cos_f32_e32 v127, v127
	v_sin_f32_e32 v144, v146
	v_sin_f32_e32 v145, v147
	v_fma_f32 v150, v148, 0.15915494, -v150
	v_fma_f32 v151, v149, 0.15915494, -v151
	v_cos_f32_e32 v146, v146
	v_cos_f32_e32 v147, v147
	v_sin_f32_e32 v148, v150
	v_sin_f32_e32 v149, v151
	v_pk_mul_f32 v[20:21], v[64:65], v[20:21] op_sel_hi:[0,1]
	v_cos_f32_e32 v150, v150
	v_cos_f32_e32 v151, v151
	v_pk_mul_f32 v[42:43], v[20:21], v[92:93]
	v_mul_f32_e32 v154, 0.15915494, v152
	v_pk_mul_f32 v[20:21], v[124:125], v[42:43]
	v_floor_f32_e32 v154, v154
	v_pk_fma_f32 v[24:25], v[126:127], v[34:35], v[20:21] neg_lo:[0,0,1] neg_hi:[0,0,1]
	v_pk_mul_f32 v[20:21], v[144:145], v[30:31]
	v_cvt_pk_bf16_f32 v116, v48, v49
	v_pk_fma_f32 v[26:27], v[146:147], v[38:39], v[20:21] neg_lo:[0,0,1] neg_hi:[0,0,1]
	v_pk_mul_f32 v[20:21], v[148:149], v[28:29]
	v_cvt_pk_bf16_f32 v117, v50, v51
	v_pk_fma_f32 v[46:47], v[150:151], v[36:37], v[20:21] neg_lo:[0,0,1] neg_hi:[0,0,1]
	ds_read_b128 v[20:23], v205 offset:160
	v_fma_f32 v154, v152, 0.15915494, -v154
	s_waitcnt lgkmcnt(1)
	v_mfma_f32_32x32x16_bf16 v[0:15], v[16:19], v[116:119], v[0:15]
	v_sin_f32_e32 v152, v154
	v_cos_f32_e32 v154, v154
	v_cvt_pk_bf16_f32 v120, v24, v25
	v_cvt_pk_bf16_f32 v121, v26, v27
	v_pk_mul_f32 v[16:17], v[152:153], v[44:45]
	v_cvt_pk_bf16_f32 v122, v46, v47
	v_pk_fma_f32 v[16:17], v[154:155], v[40:41], v[16:17] neg_lo:[0,0,1] neg_hi:[0,0,1]
	v_cvt_pk_bf16_f32 v113, v52, v53
	v_cvt_pk_bf16_f32 v123, v16, v17
	ds_read_b128 v[16:19], v205 offset:192
	v_cvt_pk_bf16_f32 v114, v54, v55
	s_waitcnt lgkmcnt(1)
	v_mfma_f32_32x32x16_bf16 v[0:15], v[20:23], v[120:123], v[0:15]
	v_mul_f32_e64 v20, v126, v42
	v_mul_f32_e64 v21, v127, v43
	v_cvt_pk_bf16_f32 v115, v32, v33
	v_fma_f32 v24, v124, v34, v20
	v_fma_f32 v25, v125, v35, v21
	v_pk_mul_f32 v[20:21], v[146:147], v[30:31]
	v_pk_mul_f32 v[28:29], v[150:151], v[28:29]
	v_pk_fma_f32 v[26:27], v[144:145], v[38:39], v[20:21]
	ds_read_b128 v[20:23], v205 offset:224
	s_waitcnt lgkmcnt(1)
	v_mfma_f32_32x32x16_bf16 v[0:15], v[16:19], v[112:115], v[0:15]
	v_mul_f32_e64 v18, v154, v44
	v_mul_f32_e64 v19, v155, v45
	v_fma_f32 v16, v148, v36, v28
	v_fma_f32 v17, v149, v37, v29
	v_fma_f32 v18, v152, v40, v18
	v_fma_f32 v19, v153, v41, v19
	v_cvt_pk_bf16_f32 v126, v16, v17
	v_cvt_pk_bf16_f32 v127, v18, v19
	ds_read_b128 v[16:19], v205 offset:8704
	ds_read_b128 v[32:35], v205 offset:8736
	v_cvt_pk_bf16_f32 v124, v24, v25
	v_cvt_pk_bf16_f32 v125, v26, v27
	v_mad_i64_i32 v[174:175], s[24:25], s42, v212, v[162:163]
	s_waitcnt lgkmcnt(2)
	v_mfma_f32_32x32x16_bf16 v[0:15], v[20:23], v[124:127], v[0:15]
	s_add_u32 s24, s20, s22
	s_addc_u32 s25, s21, s23
	s_mov_b32 s42, -1
	v_mov_b32_e32 v50, v165
	v_mov_b32_e32 v51, v165
	v_mov_b32_e32 v52, v165
	v_mov_b32_e32 v53, v165
	s_waitcnt lgkmcnt(1)
	v_mfma_f32_32x32x16_bf16 v[16:31], v[16:19], v[100:103], 0
	s_nop 2
	v_exp_f32_e32 v44, v0
	v_exp_f32_e32 v45, v1
	v_exp_f32_e32 v46, v2
	v_exp_f32_e32 v47, v3
	v_exp_f32_e32 v4, v4
	v_exp_f32_e32 v5, v5
	v_exp_f32_e32 v6, v6
	s_waitcnt lgkmcnt(0)
	v_mfma_f32_32x32x16_bf16 v[16:31], v[32:35], v[108:111], v[16:31]
	ds_read_b128 v[32:35], v205 offset:8768
	ds_read_b128 v[36:39], v205 offset:8800
	v_exp_f32_e32 v7, v7
	v_pk_add_f32 v[48:49], v[44:45], 0 op_sel_hi:[1,0]
	v_cvt_pk_bf16_f32 v80, v44, v45
	v_pk_add_f32 v[44:45], v[46:47], v[48:49]
	v_exp_f32_e32 v8, v8
	v_exp_f32_e32 v9, v9
	s_waitcnt lgkmcnt(1)
	v_mfma_f32_32x32x16_bf16 v[16:31], v[32:35], v[96:99], v[16:31]
	ds_read_b128 v[32:35], v205 offset:8832
	ds_read_b128 v[40:43], v205 offset:8864
	v_exp_f32_e32 v10, v10
	v_exp_f32_e32 v11, v11
	v_cvt_pk_bf16_f32 v146, v4, v5
	v_cvt_pk_bf16_f32 v147, v6, v7
	v_cvt_pk_bf16_f32 v145, v46, v47
	v_cvt_pk_bf16_f32 v84, v8, v9
	s_waitcnt lgkmcnt(2)
	v_mfma_f32_32x32x16_bf16 v[16:31], v[36:39], v[104:107], v[16:31]
	ds_read_b128 v[0:3], v205 offset:8896
	ds_read_b128 v[36:39], v205 offset:8928
	s_waitcnt lgkmcnt(0)
	s_barrier
; DI unsigned cvtpk(float lo, float hi) { f32x2 v = {lo, hi}; return __builtin_bit_cast(unsigned, __builtin_convertvector(v, bf16x2_t)); }
; #define B_LOADK(Kb_, tile_) do { const char* kp_ = (const char*)(Kb_) + (size_t)(tile_) * (64 * LDK * 2); const unsigned ko_ = ((tile_) == NT - 1) ? koffL : koff; \
;     _Pragma("unroll") for (int i_ = 0; i_ < NKC; ++i_) rk[i_] = *(const u32x4*)(kp_ + ko_ + i_ * 128); } while (0)
; #define B_LOADV(Vb_, tile_) do { const char* vp_ = (const char*)(Vb_) + (size_t)(tile_) * 128; \
;     rv[0] = *(const u32x4*)(vp_ + voff); rv[1] = *(const u32x4*)(vp_ + voff + 64 * LP * 2); } while (0)
; template <int NHQ, int NHKV>
; DI void attn_phase_l1(const u16* __restrict__ Q, const u16* __restrict__ K, const u16* __restrict__ Vt, u16* __restrict__ O, const float* __restrict__ qg, char* smem, const int wv) {
;     ...
;     float l = 0.f;
; #pragma unroll
;     for (int d = 0; d < 4; ++d)
; #pragma unroll
;       for (int i = 0; i < 16; ++i) o[d][i] = 0.f;
;     __syncthreads();
;     B_LOADK(Kb, 0); B_WRITEK(0); B_LOADK(Kb, 1); B_WRITEK(1); B_LOADV(Vb, 0); B_WRITEV(0);
;     B_LOADK(Kb, 2); B_LOADV(Vb, 1);
;     __syncthreads();
;     {
;       const char* sk = kb0 + r32 * KSTR + hh * 16;
; #pragma unroll
;       for (int i = 0; i < 16; ++i) { s0[i] = 0.f; s1[i] = 0.f; }
; #pragma unroll
;       for (int i = 0; i < NS; ++i) {
;         const bf16x8 k0f = *(const bf16x8*)(sk + i * 32), k1f = *(const bf16x8*)(sk + 32 * KSTR + i * 32);
;         s0 = __builtin_amdgcn_mfma_f32_32x32x16_bf16(k0f, qf[i], s0, 0, 0, 0);
;         s1 = __builtin_amdgcn_mfma_f32_32x32x16_bf16(k1f, qf[i], s1, 0, 0, 0);
;       }
;       unsigned w_[16]; f32x2 ps2 = {0.f, 0.f};
; #pragma unroll
;       for (int i = 0; i < 8; ++i) { f32x2 v; v[0] = __builtin_amdgcn_exp2f(s0[2 * i]); v[1] = __builtin_amdgcn_exp2f(s0[2 * i + 1]); ps2 += v; w_[i] = cvtpk(v[0], v[1]); }
; #pragma unroll
;       for (int i = 0; i < 8; ++i) { f32x2 v; v[0] = __builtin_amdgcn_exp2f(s1[2 * i]); v[1] = __builtin_amdgcn_exp2f(s1[2 * i + 1]); ps2 += v; w_[8 + i] = cvtpk(v[0], v[1]); }
;       l += ps2[0] + ps2[1];
; #pragma unroll
;       for (int q = 0; q < 4; ++q) pb[q] = __builtin_bit_cast(bf16x8, u32x4{w_[4 * q], w_[4 * q + 1], w_[4 * q + 2], w_[4 * q + 3]});
;     }
	v_cvt_pk_bf16_f32 v149, v10, v11
	v_mov_b32_e32 v48, v165
	v_mov_b32_e32 v49, v165
	s_waitcnt lgkmcnt(3)
	v_mfma_f32_32x32x16_bf16 v[16:31], v[32:35], v[116:119], v[16:31]
	v_add_f32_e64 v32, v4, v44
	v_add_f32_e64 v33, v5, v45
	v_mov_b32_e32 v54, v165
	v_add_f32_e64 v4, v6, v32
	v_add_f32_e64 v5, v7, v33
	v_exp_f32_e32 v6, v12
	v_exp_f32_e32 v7, v13
	v_pk_add_f32 v[4:5], v[8:9], v[4:5]
	v_mov_b32_e32 v55, v165
	s_waitcnt lgkmcnt(2)
	v_mfma_f32_32x32x16_bf16 v[16:31], v[40:43], v[120:123], v[16:31]
	v_add_f32_e64 v4, v10, v4
	v_add_f32_e64 v5, v11, v5
	v_cvt_pk_bf16_f32 v150, v6, v7
	v_mov_b32_e32 v56, v165
	v_mov_b32_e32 v57, v165
	v_mov_b32_e32 v58, v165
	v_mov_b32_e32 v59, v165
	v_mov_b32_e32 v60, v165
	s_waitcnt lgkmcnt(1)
	v_mfma_f32_32x32x16_bf16 v[16:31], v[0:3], v[112:115], v[16:31]
	v_exp_f32_e32 v0, v14
	v_exp_f32_e32 v1, v15
	v_pk_add_f32 v[2:3], v[6:7], v[4:5]
	v_mov_b32_e32 v61, v165
	v_mov_b32_e32 v62, v165
	v_pk_add_f32 v[2:3], v[0:1], v[2:3]
	v_cvt_pk_bf16_f32 v151, v0, v1
	s_waitcnt lgkmcnt(0)
	v_mfma_f32_32x32x16_bf16 v[16:31], v[36:39], v[124:127], v[16:31]
	v_mov_b32_e32 v63, v165
	v_mov_b32_e32 v32, v165
	v_mov_b32_e32 v33, v165
	v_mov_b32_e32 v34, v165
	v_mov_b32_e32 v35, v165
	v_mov_b32_e32 v36, v165
	v_mov_b32_e32 v37, v165
	s_nop 4
	v_exp_f32_e32 v4, v16
	v_exp_f32_e32 v5, v17
	v_exp_f32_e32 v6, v18
	v_exp_f32_e32 v7, v19
	v_mov_b32_e32 v38, v165
	v_pk_add_f32 v[0:1], v[2:3], v[4:5]
	v_exp_f32_e32 v2, v20
	v_exp_f32_e32 v3, v21
	v_cvt_pk_bf16_f32 v88, v4, v5
	v_pk_add_f32 v[0:1], v[6:7], v[0:1]
	v_exp_f32_e32 v4, v22
	v_exp_f32_e32 v5, v23
	v_pk_add_f32 v[0:1], v[2:3], v[0:1]
	v_cvt_pk_bf16_f32 v154, v2, v3
	v_exp_f32_e32 v2, v24
	v_exp_f32_e32 v3, v25
	v_cvt_pk_bf16_f32 v153, v6, v7
	v_pk_add_f32 v[0:1], v[4:5], v[0:1]
	v_exp_f32_e32 v6, v26
	v_exp_f32_e32 v7, v27
	v_pk_add_f32 v[0:1], v[2:3], v[0:1]
	v_cvt_pk_bf16_f32 v92, v2, v3
	v_exp_f32_e32 v2, v28
	v_exp_f32_e32 v3, v29
	v_cvt_pk_bf16_f32 v155, v4, v5
	v_exp_f32_e32 v4, v30
	v_exp_f32_e32 v5, v31
	v_pk_add_f32 v[0:1], v[6:7], v[0:1]
	v_cvt_pk_bf16_f32 v157, v6, v7
	v_pk_add_f32 v[0:1], v[2:3], v[0:1]
	v_cvt_pk_bf16_f32 v158, v2, v3
	v_pk_add_f32 v[0:1], v[4:5], v[0:1]
	v_cvt_pk_bf16_f32 v159, v4, v5
	v_add_f32_e32 v0, v0, v1
	v_add_f32_e32 v176, 0, v0
	v_mov_b32_e32 v39, v165
	v_mov_b32_e32 v40, v165
	v_mov_b32_e32 v41, v165
	v_mov_b32_e32 v42, v165
	v_mov_b32_e32 v43, v165
	v_mov_b32_e32 v44, v165
	v_mov_b32_e32 v45, v165
	v_mov_b32_e32 v46, v165
	v_mov_b32_e32 v47, v165
	v_mov_b32_e32 v16, v165
	v_mov_b32_e32 v17, v165
	v_mov_b32_e32 v18, v165
	v_mov_b32_e32 v19, v165
	v_mov_b32_e32 v20, v165
	v_mov_b32_e32 v21, v165
	v_mov_b32_e32 v22, v165
	v_mov_b32_e32 v23, v165
	v_mov_b32_e32 v24, v165
	v_mov_b32_e32 v25, v165
	v_mov_b32_e32 v26, v165
	v_mov_b32_e32 v27, v165
	v_mov_b32_e32 v28, v165
	v_mov_b32_e32 v29, v165
	v_mov_b32_e32 v30, v165
	v_mov_b32_e32 v31, v165
	v_mov_b32_e32 v0, v165
	v_mov_b32_e32 v1, v165
	v_mov_b32_e32 v2, v165
	v_mov_b32_e32 v3, v165
	v_mov_b32_e32 v4, v165
	v_mov_b32_e32 v5, v165
	v_mov_b32_e32 v6, v165
	v_mov_b32_e32 v7, v165
	v_mov_b32_e32 v8, v165
	v_mov_b32_e32 v9, v165
	v_mov_b32_e32 v10, v165
	v_mov_b32_e32 v11, v165
	v_mov_b32_e32 v12, v165
	v_mov_b32_e32 v13, v165
	v_mov_b32_e32 v14, v165
	v_mov_b32_e32 v15, v165
	s_cmp_ge_u32 s3, 4
	s_cbranch_scc1 .Lb_first

; template <int NHQ, int NHKV>
; DI void attn_phase_l1(const u16* __restrict__ Q, const u16* __restrict__ K, const u16* __restrict__ Vt, u16* __restrict__ O, const float* __restrict__ qg, char* smem, const int wv) {
;     ...
;     for (int j = 0; j < NT; ++j) {
;       if (j + 2 < NT) B_WRITEK(j & 1);
;       if (j + 1 < NT) B_WRITEV((j + 1) & 1);
;       __builtin_amdgcn_sched_barrier(0);
;       if (j + 3 < NT) B_LOADK(Kb, j + 3);
;       if (j + 2 < NT) B_LOADV(Vb, j + 2);
;       __builtin_amdgcn_sched_barrier(0);
;       if (j == NT - 1) {
;         const char* svl = vb0 + (j & 1) * VBYTES + r32 * VSTR + hh * 16;
;         bf16x8 vf[4];
; #pragma unroll
;         for (int d = 0; d < 4; ++d) vf[d] = *(const bf16x8*)(svl + d * 32 * VSTR);
; #pragma unroll
;         for (int d = 0; d < 4; ++d) o[d] = __builtin_amdgcn_mfma_f32_32x32x16_bf16(vf[d], pb[0], o[d], 0, 0, 0);
;       } else {
;         constexpr int NQK = 2 * NS, NM = NQK + 16, RING = 8;
;         const char* sk = kb0 + ((j + 1) & 1) * KBYTES + r32 * KSTR + hh * 16;
;         const char* sv = vb0 + (j & 1) * VBYTES + r32 * VSTR + hh * 16;
;         bf16x8 ring[RING];
;         unsigned w_[16]; f32x2 ps2 = {0.f, 0.f};
;     ...
; #pragma unroll
;         for (int i = 0; i < 16; ++i) { s0[i] = 0.f; s1[i] = 0.f; }
; #pragma unroll
;         for (int i = 0; i < RING; ++i) B_FRAG(ring[i], i);
; #pragma unroll
;         for (int i = 0; i < NM; ++i) {
;           if (i < NQK) {
;             if (i & 1) s1 = __builtin_amdgcn_mfma_f32_32x32x16_bf16(ring[i % RING], qf[i >> 1], s1, 0, 0, 0);
;             else       s0 = __builtin_amdgcn_mfma_f32_32x32x16_bf16(ring[i % RING], qf[i >> 1], s0, 0, 0, 0);
;           } else {
;             o[(i - NQK) & 3] = __builtin_amdgcn_mfma_f32_32x32x16_bf16(ring[i % RING], pb[(i - NQK) >> 2], o[(i - NQK) & 3], 0, 0, 0);
;           }
;           if (i + RING < NM) B_FRAG(ring[i % RING], i + RING);
;           if (i >= NQK + 2) {
;             const int g = i - NQK - 2;
;             f32x2 v;
;             if (g < 8) { v[0] = __builtin_amdgcn_exp2f(s0[2 * g]); v[1] = __builtin_amdgcn_exp2f(s0[2 * g + 1]); }
;             else       { v[0] = __builtin_amdgcn_exp2f(s1[2 * (g - 8)]); v[1] = __builtin_amdgcn_exp2f(s1[2 * (g - 8) + 1]); }
;             ps2 += v; w_[g] = cvtpk(v[0], v[1]);
;           }
;           __builtin_amdgcn_sched_barrier(0);
;         }
; #pragma unroll
.Lb_first:
	v_mov_b32_e32 v156, v92
	v_mov_b32_e32 v152, v88
	v_mov_b32_e32 v148, v84
	v_mov_b32_e32 v144, v80
	s_branch .Lb_body
.Lb_top:
	s_nop 7
	v_exp_f32_e32 v80, v80
	v_exp_f32_e32 v81, v81
	s_nop 0
	v_mov_b32_e32 v198, v80
	v_mov_b32_e32 v199, v81
	v_cvt_pk_bf16_f32 v144, v80, v81
	v_exp_f32_e32 v82, v82
	v_exp_f32_e32 v83, v83
	s_nop 0
	v_cvt_pk_bf16_f32 v145, v82, v83
	v_add_f32_e32 v198, v82, v198
	v_add_f32_e32 v199, v83, v199
	v_exp_f32_e32 v82, v84
	v_exp_f32_e32 v83, v85
	s_nop 0
	v_add_f32_e32 v84, v82, v198
	v_add_f32_e32 v85, v83, v199
	v_cvt_pk_bf16_f32 v146, v82, v83
	v_exp_f32_e32 v82, v86
	v_exp_f32_e32 v83, v87
	s_nop 0
	v_add_f32_e32 v84, v82, v84
	v_add_f32_e32 v85, v83, v85
	v_cvt_pk_bf16_f32 v147, v82, v83
	v_exp_f32_e32 v82, v88
	v_exp_f32_e32 v83, v89
	s_nop 0
	v_add_f32_e32 v86, v82, v84
	v_add_f32_e32 v87, v83, v85
	v_cvt_pk_bf16_f32 v148, v82, v83
	v_exp_f32_e32 v82, v90
	v_exp_f32_e32 v83, v91
	s_nop 0
	v_cvt_pk_bf16_f32 v149, v82, v83
	v_add_f32_e32 v86, v82, v86
	v_add_f32_e32 v87, v83, v87
	v_exp_f32_e32 v82, v92
	v_exp_f32_e32 v83, v93
	s_nop 0
	v_cvt_pk_bf16_f32 v150, v82, v83
	v_add_f32_e32 v86, v82, v86
	v_add_f32_e32 v87, v83, v87
	v_exp_f32_e32 v82, v94
	v_exp_f32_e32 v83, v95
	s_nop 0
	v_cvt_pk_bf16_f32 v151, v82, v83
	v_add_f32_e32 v86, v82, v86
	v_add_f32_e32 v87, v83, v87
	v_exp_f32_e32 v64, v64
	v_exp_f32_e32 v65, v65
	s_nop 0
	v_cvt_pk_bf16_f32 v152, v64, v65
	v_add_f32_e32 v82, v64, v86
	v_add_f32_e32 v83, v65, v87
	v_exp_f32_e32 v64, v66
	v_exp_f32_e32 v65, v67
	s_nop 0
	v_cvt_pk_bf16_f32 v153, v64, v65
	v_add_f32_e32 v66, v64, v82
	v_add_f32_e32 v67, v65, v83
	v_exp_f32_e32 v64, v68
	v_exp_f32_e32 v65, v69
	s_nop 0
	v_cvt_pk_bf16_f32 v154, v64, v65
	v_add_f32_e32 v66, v64, v66
	v_add_f32_e32 v67, v65, v67
	v_exp_f32_e32 v64, v70
	v_exp_f32_e32 v65, v71
	s_nop 0
	v_cvt_pk_bf16_f32 v155, v64, v65
	v_add_f32_e32 v66, v64, v66
	v_add_f32_e32 v67, v65, v67
	v_exp_f32_e32 v64, v72
	v_exp_f32_e32 v65, v73
	s_nop 0
	v_cvt_pk_bf16_f32 v156, v64, v65
	v_add_f32_e32 v66, v64, v66
	v_add_f32_e32 v67, v65, v67
	v_exp_f32_e32 v64, v74
	v_exp_f32_e32 v65, v75
	s_nop 0
	v_cvt_pk_bf16_f32 v157, v64, v65
	v_add_f32_e32 v64, v64, v66
	v_add_f32_e32 v65, v65, v67
	v_exp_f32_e32 v66, v76
	v_exp_f32_e32 v67, v77
	v_exp_f32_e32 v68, v78
	v_exp_f32_e32 v69, v79
	s_nop 0
	v_add_f32_e32 v64, v66, v64
	v_add_f32_e32 v65, v67, v65
	v_add_f32_e32 v64, v68, v64
	v_add_f32_e32 v65, v69, v65
	v_add_f32_e32 v64, v64, v65
	v_cvt_pk_bf16_f32 v158, v66, v67
	v_cvt_pk_bf16_f32 v159, v68, v69
	v_add_f32_e32 v176, v176, v64
.Lb_body:
	s_add_i32 s27, s42, 1
	s_bitcmp1_b32 s27, 0
	s_cselect_b64 s[20:21], -1, 0
	s_and_b64 s[22:23], s[20:21], exec
	s_cselect_b32 s26, 0x4400, 0
	s_bitcmp1_b32 s42, 0
	s_cselect_b64 s[22:23], -1, 0
	s_and_b64 s[44:45], s[22:23], exec
	s_cselect_b32 s43, 0x4800, 0
	s_and_b64 s[22:23], s[22:23], exec
	s_cselect_b32 s22, 0x4400, 0
	v_add_u32_e32 v164, s22, v205
	ds_read_b128 v[64:67], v164
	ds_read_b128 v[178:181], v164 offset:32
	ds_read_b128 v[182:185], v164 offset:8736
	ds_read_b128 v[186:189], v164 offset:8768
	ds_read_b128 v[190:193], v164 offset:64
	ds_read_b128 v[194:197], v164 offset:96
	ds_read_b128 v[214:217], v164 offset:8800
	s_waitcnt lgkmcnt(6)
	v_mfma_f32_32x32x16_bf16 v[80:95], v[64:67], v[100:103], 0
	ds_read_b128 v[68:71], v164 offset:8704
	ds_read_b128 v[220:223], v164 offset:128
	s_and_b64 s[20:21], s[20:21], exec
	s_cselect_b32 s20, 0x4800, 0
	v_add_u32_e32 v177, s20, v206
	ds_read_b128 v[224:227], v164 offset:8832
	s_waitcnt lgkmcnt(2)
	v_mfma_f32_32x32x16_bf16 v[64:79], v[68:71], v[100:103], 0
	v_mfma_f32_32x32x16_bf16 v[80:95], v[178:181], v[108:111], v[80:95]
	ds_read_b128 v[228:231], v164 offset:160
	ds_read_b128 v[178:181], v164 offset:8864
	s_waitcnt vmcnt(0)
	v_add_u32_e32 v238, s26, v203
	ds_write_b128 v238, v[128:131]
	v_mfma_f32_32x32x16_bf16 v[64:79], v[182:185], v[108:111], v[64:79]
	ds_write_b128 v238, v[132:135] offset:128
	v_mfma_f32_32x32x16_bf16 v[80:95], v[190:193], v[96:99], v[80:95]
	ds_read_b128 v[182:185], v164 offset:192
	ds_read_b128 v[190:193], v164 offset:8896
	v_add_u32_e32 v239, s43, v204
	ds_write_b128 v239, v[136:139] offset:34816
	v_mfma_f32_32x32x16_bf16 v[64:79], v[186:189], v[96:99], v[64:79]
	ds_write_b128 v239, v[140:143] offset:44032
	v_mfma_f32_32x32x16_bf16 v[80:95], v[194:197], v[104:107], v[80:95]
	ds_read_b128 v[186:189], v164 offset:224
	ds_read_b128 v[194:197], v164 offset:8928
	s_cmp_gt_u32 s27, 61
	s_cbranch_scc1 .Lmy_b_skipk
	s_cmp_eq_u32 s42, 60
	s_cselect_b64 vcc, -1, 0
	s_add_u32 s42, s6, s24
	v_cndmask_b32_e32 v242, v160, v201, vcc
	s_addc_u32 s43, s7, s25
	v_mov_b32_e32 v243, 0
	v_lshl_add_u64 v[240:241], s[42:43], 0, v[242:243]
	v_add_co_u32_e32 v240, vcc, 0x38b18000, v240
	s_nop 1
	v_addc_co_u32_e32 v241, vcc, 0, v241, vcc
	global_load_dwordx4 v[128:131], v[240:241], off
	global_load_dwordx4 v[132:135], v[240:241], off offset:128
; template <int NHQ, int NHKV>
; DI void attn_phase_l1(const u16* __restrict__ Q, const u16* __restrict__ K, const u16* __restrict__ Vt, u16* __restrict__ O, const float* __restrict__ qg, char* smem, const int wv) {
;     ...
; #pragma unroll
;         for (int i = 0; i < 16; ++i) { s0[i] = 0.f; s1[i] = 0.f; }
; #pragma unroll
;         for (int i = 0; i < RING; ++i) B_FRAG(ring[i], i);
; #pragma unroll
;         for (int i = 0; i < NM; ++i) {
;           if (i < NQK) {
;             if (i & 1) s1 = __builtin_amdgcn_mfma_f32_32x32x16_bf16(ring[i % RING], qf[i >> 1], s1, 0, 0, 0);
;             else       s0 = __builtin_amdgcn_mfma_f32_32x32x16_bf16(ring[i % RING], qf[i >> 1], s0, 0, 0, 0);
;           } else {
;             o[(i - NQK) & 3] = __builtin_amdgcn_mfma_f32_32x32x16_bf16(ring[i % RING], pb[(i - NQK) >> 2], o[(i - NQK) & 3], 0, 0, 0);
;           }
;           if (i + RING < NM) B_FRAG(ring[i % RING], i + RING);
;           if (i >= NQK + 2) {
;             const int g = i - NQK - 2;
;             f32x2 v;
;             if (g < 8) { v[0] = __builtin_amdgcn_exp2f(s0[2 * g]); v[1] = __builtin_amdgcn_exp2f(s0[2 * g + 1]); }
;             else       { v[0] = __builtin_amdgcn_exp2f(s1[2 * (g - 8)]); v[1] = __builtin_amdgcn_exp2f(s1[2 * (g - 8) + 1]); }
;             ps2 += v; w_[g] = cvtpk(v[0], v[1]);
;           }
;           __builtin_amdgcn_sched_barrier(0);
;         }
; #pragma unroll
;         for (int g = 14; g < 16; ++g) { f32x2 v; v[0] = __builtin_amdgcn_exp2f(s1[2 * (g - 8)]); v[1] = __builtin_amdgcn_exp2f(s1[2 * (g - 8) + 1]); ps2 += v; w_[g] = cvtpk(v[0], v[1]); }
;     ...
;         if (j + 1 == NT - 1) {
;           ps2 = f32x2{0.f, 0.f};
; #pragma unroll
;           for (int g = 0; g < 4; ++g) { ps2[0] += __builtin_amdgcn_exp2f(s0[2 * g]); ps2[1] += __builtin_amdgcn_exp2f(s0[2 * g + 1]); }
; #pragma unroll
;           for (int g = 4; g < 16; ++g) w_[g] = 0u;
;         }
;         if (j + 1 < NT) {
;           l += ps2[0] + ps2[1];
; #pragma unroll
;           for (int q = 0; q < 4; ++q) pb[q] = __builtin_bit_cast(bf16x8, u32x4{w_[4 * q], w_[4 * q + 1], w_[4 * q + 2], w_[4 * q + 3]});
;         }
;       }
;       asm volatile("s_waitcnt lgkmcnt(0)" ::: "memory"); __builtin_amdgcn_s_barrier(); asm volatile("" ::: "memory");
.Lmy_b_skipk:
	v_mfma_f32_32x32x16_bf16 v[64:79], v[214:217], v[104:107], v[64:79]
	v_lshl_add_u64 v[240:241], s[6:7], 0, v[174:175]
	v_add_co_u32_e32 v244, vcc, 0x29900000, v240
	s_nop 1
	v_addc_co_u32_e32 v245, vcc, 0, v241, vcc
	v_add_co_u32_e32 v240, vcc, 0x29982000, v240
	s_nop 1
	v_addc_co_u32_e32 v241, vcc, 0, v241, vcc
	global_load_dwordx4 v[136:139], v[244:245], off offset:256
	global_load_dwordx4 v[140:143], v[240:241], off offset:256
	s_waitcnt lgkmcnt(11)
	v_mfma_f32_32x32x16_bf16 v[80:95], v[220:223], v[116:119], v[80:95]
	ds_read_b128 v[214:217], v177 offset:34816
	ds_read_b128 v[220:223], v177 offset:39424
	s_waitcnt lgkmcnt(12)
	v_mfma_f32_32x32x16_bf16 v[64:79], v[224:227], v[116:119], v[64:79]
	s_waitcnt lgkmcnt(11)
	v_mfma_f32_32x32x16_bf16 v[80:95], v[228:231], v[120:123], v[80:95]
	ds_read_b128 v[224:227], v177 offset:44032
	ds_read_b128 v[228:231], v177 offset:48640
	s_waitcnt lgkmcnt(12)
	v_mfma_f32_32x32x16_bf16 v[64:79], v[178:181], v[120:123], v[64:79]
	s_waitcnt lgkmcnt(9)
	v_mfma_f32_32x32x16_bf16 v[80:95], v[182:185], v[112:115], v[80:95]
	ds_read_b128 v[178:181], v177 offset:34848
	ds_read_b128 v[182:185], v177 offset:39456
	s_waitcnt lgkmcnt(10)
	v_mfma_f32_32x32x16_bf16 v[64:79], v[190:193], v[112:115], v[64:79]
	s_waitcnt lgkmcnt(7)
	v_mfma_f32_32x32x16_bf16 v[80:95], v[186:189], v[124:127], v[80:95]
	ds_read_b128 v[190:193], v177 offset:44064
	ds_read_b128 v[186:189], v177 offset:48672
	s_waitcnt lgkmcnt(8)
	v_mfma_f32_32x32x16_bf16 v[64:79], v[194:197], v[124:127], v[64:79]
	s_waitcnt lgkmcnt(7)
	v_mfma_f32_32x32x16_bf16 v[48:63], v[214:217], v[144:147], v[48:63]
	ds_read_b128 v[194:197], v177 offset:34880
	s_waitcnt lgkmcnt(7)
	v_mfma_f32_32x32x16_bf16 v[32:47], v[220:223], v[144:147], v[32:47]
	ds_read_b128 v[214:217], v177 offset:39488
	s_waitcnt lgkmcnt(7)
	v_mfma_f32_32x32x16_bf16 v[16:31], v[224:227], v[144:147], v[16:31]
	ds_read_b128 v[220:223], v177 offset:44096
	s_waitcnt lgkmcnt(7)
	v_mfma_f32_32x32x16_bf16 v[0:15], v[228:231], v[144:147], v[0:15]
	ds_read_b128 v[224:227], v177 offset:48704
	s_waitcnt lgkmcnt(7)
	v_mfma_f32_32x32x16_bf16 v[48:63], v[178:181], v[148:151], v[48:63]
	ds_read_b128 v[228:231], v177 offset:34912
	s_waitcnt lgkmcnt(7)
	v_mfma_f32_32x32x16_bf16 v[32:47], v[182:185], v[148:151], v[32:47]
	ds_read_b128 v[178:181], v177 offset:39520
	s_waitcnt lgkmcnt(7)
	v_mfma_f32_32x32x16_bf16 v[16:31], v[190:193], v[148:151], v[16:31]
	ds_read_b128 v[182:185], v177 offset:44128
	s_waitcnt lgkmcnt(7)
	v_mfma_f32_32x32x16_bf16 v[0:15], v[186:189], v[148:151], v[0:15]
	ds_read_b128 v[190:193], v177 offset:48736
	s_waitcnt lgkmcnt(7)
	v_mfma_f32_32x32x16_bf16 v[48:63], v[194:197], v[152:155], v[48:63]
	s_waitcnt lgkmcnt(6)
	v_mfma_f32_32x32x16_bf16 v[32:47], v[214:217], v[152:155], v[32:47]
	s_waitcnt lgkmcnt(5)
	v_mfma_f32_32x32x16_bf16 v[16:31], v[220:223], v[152:155], v[16:31]
	s_waitcnt lgkmcnt(4)
	v_mfma_f32_32x32x16_bf16 v[0:15], v[224:227], v[152:155], v[0:15]
	s_waitcnt lgkmcnt(3)
	v_mfma_f32_32x32x16_bf16 v[48:63], v[228:231], v[156:159], v[48:63]
	s_waitcnt lgkmcnt(2)
	v_mfma_f32_32x32x16_bf16 v[32:47], v[178:181], v[156:159], v[32:47]
	s_waitcnt lgkmcnt(1)
	v_mfma_f32_32x32x16_bf16 v[16:31], v[182:185], v[156:159], v[16:31]
	s_waitcnt lgkmcnt(0)
	v_mfma_f32_32x32x16_bf16 v[0:15], v[190:193], v[156:159], v[0:15]
	s_waitcnt lgkmcnt(0)
	s_barrier
	s_add_u32 s24, s24, 0x8000
	s_addc_u32 s25, s25, 0
	s_cmp_eq_u32 s27, 62
	v_lshl_add_u64 v[174:175], v[174:175], 0, s[16:17]
	s_cbranch_scc1 .Lb_exit
	s_mov_b32 s42, s27
	s_branch .Lb_top
.Lb_exit:
	s_nop 7
	v_exp_f32_e32 v80, v80
	v_exp_f32_e32 v81, v81
	s_nop 0
	v_mov_b32_e32 v198, v80
	v_mov_b32_e32 v199, v81
	v_cvt_pk_bf16_f32 v80, v80, v81
	v_exp_f32_e32 v82, v82
	v_exp_f32_e32 v83, v83
	s_nop 0
	v_cvt_pk_bf16_f32 v145, v82, v83
	v_add_f32_e32 v198, v82, v198
	v_add_f32_e32 v199, v83, v199
	v_exp_f32_e32 v82, v84
	v_exp_f32_e32 v83, v85
	s_nop 0
	v_add_f32_e32 v84, v82, v198
	v_add_f32_e32 v85, v83, v199
	v_cvt_pk_bf16_f32 v146, v82, v83
	v_exp_f32_e32 v82, v86
	v_exp_f32_e32 v83, v87
	s_nop 0
	v_add_f32_e32 v84, v82, v84
	v_add_f32_e32 v85, v83, v85
	v_cvt_pk_bf16_f32 v147, v82, v83
	v_exp_f32_e32 v82, v88
	v_exp_f32_e32 v83, v89
	s_nop 0
	v_add_f32_e32 v86, v82, v84
	v_add_f32_e32 v87, v83, v85
	v_cvt_pk_bf16_f32 v84, v82, v83
	v_exp_f32_e32 v82, v90
	v_exp_f32_e32 v83, v91
	s_nop 0
	v_cvt_pk_bf16_f32 v149, v82, v83
	v_add_f32_e32 v86, v82, v86
	v_add_f32_e32 v87, v83, v87
	v_exp_f32_e32 v82, v92
	v_exp_f32_e32 v83, v93
	s_nop 0
	v_cvt_pk_bf16_f32 v150, v82, v83
	v_add_f32_e32 v86, v82, v86
	v_add_f32_e32 v87, v83, v87
	v_exp_f32_e32 v82, v94
	v_exp_f32_e32 v83, v95
	s_nop 0
	v_cvt_pk_bf16_f32 v151, v82, v83
	v_add_f32_e32 v86, v82, v86
	v_add_f32_e32 v87, v83, v87
	v_exp_f32_e32 v64, v64
	v_exp_f32_e32 v65, v65
	s_nop 0
	v_cvt_pk_bf16_f32 v88, v64, v65
	v_add_f32_e32 v82, v64, v86
	v_add_f32_e32 v83, v65, v87
	v_exp_f32_e32 v64, v66
	v_exp_f32_e32 v65, v67
	s_nop 0
	v_cvt_pk_bf16_f32 v153, v64, v65
	v_add_f32_e32 v66, v64, v82
	v_add_f32_e32 v67, v65, v83
	v_exp_f32_e32 v64, v68
	v_exp_f32_e32 v65, v69
	s_nop 0
	v_cvt_pk_bf16_f32 v154, v64, v65
	v_add_f32_e32 v66, v64, v66
	v_add_f32_e32 v67, v65, v67
	v_exp_f32_e32 v64, v70
	v_exp_f32_e32 v65, v71
	s_nop 0
	v_cvt_pk_bf16_f32 v155, v64, v65
	v_add_f32_e32 v66, v64, v66
	v_add_f32_e32 v67, v65, v67
	v_exp_f32_e32 v64, v72
	v_exp_f32_e32 v65, v73
	s_nop 0
	v_cvt_pk_bf16_f32 v92, v64, v65
	v_add_f32_e32 v66, v64, v66
	v_add_f32_e32 v67, v65, v67
	v_exp_f32_e32 v64, v74
	v_exp_f32_e32 v65, v75
	s_nop 0
	v_cvt_pk_bf16_f32 v157, v64, v65
	v_add_f32_e32 v64, v64, v66
	v_add_f32_e32 v65, v65, v67
	v_exp_f32_e32 v66, v76
	v_exp_f32_e32 v67, v77
	v_exp_f32_e32 v68, v78
	v_exp_f32_e32 v69, v79
	s_nop 0
	v_add_f32_e32 v64, v66, v64
	v_add_f32_e32 v65, v67, v65
	v_add_f32_e32 v64, v68, v64
	v_add_f32_e32 v65, v69, v65
	v_add_f32_e32 v64, v64, v65
	v_cvt_pk_bf16_f32 v158, v66, v67
	v_cvt_pk_bf16_f32 v159, v68, v69
	v_add_f32_e32 v176, v176, v64
	s_branch .LBB0_1215
